# nowait_mma + NA main tile loop VALU trim (-16 VALU per tile: folded bias/V address math, packed score-minus-max subs, row-sum init, alpha copy)
# speedup vs baseline: 1.0094x; 1.0047x over previous
; #define LAS __attribute__((address_space(3)))
; template <int MODE> ...
;     ...
;             for (int jj = 0; jj < 2; ++jj) { const LAS f32x4* bl = bcp + ((MODE == 0) ? (dr0 + t - act0) * 8 : 16 * t + 8 * hf) + bofs[jj];
; #pragma unroll
;                 for (int kt = 0; kt < 2; ++kt) bb[jj][kt] = bl[4 * kt]; }
;             s16x4 vlo[2][4], vhi[2][4];
; #pragma unroll
;             for (int jj = 0; jj < 2; ++jj)
; #pragma unroll
;                 for (int dt = 0; dt < 4; ++dt) { const LAS unsigned char* vp = Sl + vad[jj] + (32 * hf) * 128 + ((dt ^ sv) << 5);
; __global__ void __launch_bounds__(NWAVES * 64, 2) fwd_kernel(Args args) {
;     ...
;                 const int r4 = n & 63, h = (n >> 6) & 7, sq = n >> 9; const int r0 = 4 * r4, r = r0 + (wave >> 1);
;                 const int rs0 = min(max(r0 - 4, 0), 248), rs3 = min(max(r0 - 1, 0), 248), rs = min(max(r - 4, 0), 248);
;                 const char* nK = nullptr; const char* nV = nullptr;
;                 const bf16_t* nQ = nullptr;
;                 if (n + G < 1536) { kbase_n(n + G, nK, nV); const int n2 = n + G; nQ = PROJ + (size_t)((n2 >> 9) * SEQ + (4 * (n2 & 63) + (wave >> 1)) * 64 + 32 * (wave & 1)) * NIN + COL_QA + ((n2 >> 6) & 7) * 64; }
;                 else if (REP_MASK == 0 && vcu < 1536) { kbase_s(vcu, nK, nV); const int n2 = vcu; nQ = PROJ + (size_t)((n2 >> 9) * SEQ + 64 * (n2 & 255) + 32 * (wave >> 2)) * NIN + COL_QB + (4 * ((n2 >> 8) & 1) + (wave & 3)) * 64; }
;                 att::block_unit<0>(lds, PROJ, ATT, SSA, lane, wave, sq * SEQ + rs0 * 64, rs3 + 8 - rs0, COL_KA + h * 64, COL_VA + h * 64, rs - rs0, 8,
;                                    sq * SEQ + r * 64 + 32 * (wave & 1), wave & 1, COL_QA + h * 64, cpy + h * 120, rs - r + 7, 0.f, 0.f, h * 64, h, rbase, pre, nK, nV, nQ, qf);
.LBB0_299:
	s_and_b32 s14, s5, 0xfc
	s_lshr_b32 s0, s45, 6
	s_min_u32 s15, s14, 4
	s_and_b32 s0, s0, 7
	s_add_i32 s50, s90, s15
	s_mulk_i32 s0, 0x780
	s_lshl_b32 s50, s50, 7
	s_sub_i32 s0, s0, s50
	v_sub_u32_e64 v0, s14, 1 clamp
	s_add_i32 s50, s0, 0x10480
	v_readfirstlane_b32 s0, v0
	s_min_u32 s0, s0, 0xf8
	s_sub_i32 s51, s14, s0
	s_add_i32 s0, s0, s15
	s_sub_i32 s51, s51, s15
	s_sub_i32 s52, s0, s14
	s_lshl_b32 s0, s86, 14
	v_readlane_b32 s14, v254, 60
	s_add_i32 s45, s23, 8
	s_add_i32 s51, s51, -4
	s_add_i32 s52, s52, 5
	s_add_i32 s53, s14, s0
	s_add_i32 s64, s86, 4
	s_add_u32 s46, s46, 0x120000
	s_addc_u32 s47, s47, 0
	s_add_u32 s42, s42, 0x120000
	v_add_u32_e32 v0, v86, v122
	v_add_u32_e32 v126, v123, v122
	v_add_u32_e32 v178, v0, v94
	v_add_u32_e32 v179, v0, v95
	v_add_u32_e32 v180, v0, v96
	v_add_u32_e32 v181, v0, v97
	v_add_u32_e32 v182, v126, v94
	v_add_u32_e32 v183, v126, v95
	v_add_u32_e32 v184, v126, v96
	v_add_u32_e32 v185, v126, v97
	v_lshlrev_b32_e32 v127, 4, v90
	v_lshlrev_b32_e32 v128, 4, v87
	s_addc_u32 s43, s43, 0
	s_mov_b32 s65, 0
	s_branch .LBB0_301

; #define LAS __attribute__((address_space(3)))
; template <int MODE> ...
;     ...
;         if (t >= act0 && t < act0 + actn) {
;         const LAS unsigned char* Sl = ring + ((t + base) % 3) * SLOT;
; #pragma unroll
;         for (int hf = 0; hf < NH; ++hf) {
;             if (MODE == 1) { const int ks = ktok0 + 64 * t + 32 * hf;
;                 if (ks + 31 < qtok0 - 128 || ks > qtok0 + 31 + 128) continue; }
;             bf16x8 kf[2][2][2];
; #pragma unroll
;             for (int jj = 0; jj < 2; ++jj)
; #pragma unroll
;                 for (int kt = 0; kt < 2; ++kt)
; #pragma unroll
;                     for (int ks = 0; ks < 2; ++ks) kf[jj][kt][ks] = *(const LAS bf16x8*)(Sl + kad[jj][ks] + (32 * hf + 16 * kt) * 128);
;             f32x4 bb[2][2];
; #pragma unroll
;             for (int jj = 0; jj < 2; ++jj) { const LAS f32x4* bl = bcp + ((MODE == 0) ? (dr0 + t - act0) * 8 : 16 * t + 8 * hf) + bofs[jj];
; #pragma unroll
;                 for (int kt = 0; kt < 2; ++kt) bb[jj][kt] = bl[4 * kt]; }
;             s16x4 vlo[2][4], vhi[2][4];
; #pragma unroll
;             for (int jj = 0; jj < 2; ++jj)
; #pragma unroll
;                 for (int dt = 0; dt < 4; ++dt) { const LAS unsigned char* vp = Sl + vad[jj] + (32 * hf) * 128 + ((dt ^ sv) << 5);
;                     vlo[jj][dt] = __builtin_bit_cast(s16x4, __builtin_amdgcn_ds_read_tr16_b64_v4i16((LAS s16x4*)(vp)));
;                     vhi[jj][dt] = __builtin_bit_cast(s16x4, __builtin_amdgcn_ds_read_tr16_b64_v4i16((LAS s16x4*)(vp + 2048))); }
.LBB0_305:
	s_add_i32 s0, s65, 2
	s_cmp_ge_i32 s0, s23
	s_cselect_b64 s[60:61], -1, 0
	s_cmp_lt_i32 s0, s45
	s_cselect_b64 s[66:67], -1, 0
	s_and_b64 s[60:61], s[60:61], s[66:67]
	s_andn2_b64 vcc, exec, s[60:61]
	s_cbranch_vccnz .LBB0_300
	s_add_i32 s0, s86, s65
	s_add_i32 s0, s0, 2
	s_mul_hi_i32 s14, s0, 0x55555556
	s_lshr_b32 s15, s14, 31
	s_add_i32 s14, s14, s15
	s_mul_i32 s14, s14, 3
	s_sub_i32 s0, s0, s14
	s_lshl_b32 s0, s0, 14
	s_add_i32 s0, s0, 0
	v_add_u32_e32 v2, s0, v89
	v_add_u32_e32 v3, s0, v88
	ds_read_b128 v[130:133], v2
	ds_read_b128 v[134:137], v2 offset:2048
	ds_read_b128 v[138:141], v3
	ds_read_b128 v[142:145], v3 offset:2048
	v_add_u32_e32 v2, s0, v92
	v_add_u32_e32 v3, s0, v91
	ds_read_b128 v[146:149], v2
	ds_read_b128 v[150:153], v2 offset:2048
	ds_read_b128 v[154:157], v3
	ds_read_b128 v[158:161], v3 offset:2048
	v_add_u32_e32 v2, s50, v128
	v_add_u32_e32 v3, s50, v127
	ds_read_b128 v[162:165], v2
	ds_read_b128 v[166:169], v2 offset:64
	ds_read_b128 v[170:173], v3
	ds_read_b128 v[174:177], v3 offset:64
	v_add_u32_e32 v3, s0, v178
	v_add_u32_e32 v4, s0, v179
	ds_read_b64_tr_b16 v[78:79], v3 offset:8192
	ds_read_b64_tr_b16 v[80:81], v3 offset:10240
	ds_read_b64_tr_b16 v[74:75], v4 offset:8192
	ds_read_b64_tr_b16 v[76:77], v4 offset:10240
	v_add_u32_e32 v3, s0, v180
	v_add_u32_e32 v2, s0, v181
	ds_read_b64_tr_b16 v[70:71], v3 offset:8192
	ds_read_b64_tr_b16 v[72:73], v3 offset:10240
	ds_read_b64_tr_b16 v[66:67], v2 offset:8192
	ds_read_b64_tr_b16 v[68:69], v2 offset:10240
	v_add_u32_e32 v3, s0, v182
	v_add_u32_e32 v4, s0, v183
	ds_read_b64_tr_b16 v[14:15], v3 offset:8192
	ds_read_b64_tr_b16 v[16:17], v3 offset:10240
	ds_read_b64_tr_b16 v[10:11], v4 offset:8192
	ds_read_b64_tr_b16 v[12:13], v4 offset:10240
	v_add_u32_e32 v3, s0, v184
	v_add_u32_e32 v4, s0, v185
	ds_read_b64_tr_b16 v[6:7], v3 offset:8192
	ds_read_b64_tr_b16 v[8:9], v3 offset:10240
	ds_read_b64_tr_b16 v[2:3], v4 offset:8192
	ds_read_b64_tr_b16 v[4:5], v4 offset:10240
	s_waitcnt lgkmcnt(14)
; __device__ __forceinline__ unsigned cvtpk(float lo, float hi) { f32x2 v = {lo, hi}; bf16x2_t b = __builtin_convertvector(v, bf16x2_t); return __builtin_bit_cast(unsigned, b); }
; __device__ __forceinline__ float vmax3(float a, float b, float c) { return __builtin_elementwise_maximum(__builtin_elementwise_maximum(a, b), c); }
; template <int MODE> ...
;     ...
;             f32x4 s[2][2];
; #pragma unroll
;             for (int jj = 0; jj < 2; ++jj)
; #pragma unroll
;                 for (int kt = 0; kt < 2; ++kt) { f32x4 a = (MODE == 0) ? bb[jj][kt] + mneg[jj][kt] : bb[jj][kt];
;                     a = __builtin_amdgcn_mfma_f32_16x16x32_bf16(kf[jj][kt][0], qf[jj][0], a, 0, 0, 0);
;                     s[jj][kt] = __builtin_amdgcn_mfma_f32_16x16x32_bf16(kf[jj][kt][1], qf[jj][1], a, 0, 0, 0); }
;             u32x4 pw[2];
; #pragma unroll
;             for (int jj = 0; jj < 2; ++jj) {
;                 const float tm = vmax3(vmax3(s[jj][0][0], s[jj][0][1], s[jj][0][2]), vmax3(s[jj][0][3], s[jj][1][0], s[jj][1][1]), vmax3(s[jj][1][2], s[jj][1][3], s[jj][1][3]));
;                 const float mn = quad_max3(mrun[jj], tm);
;                 const float alpha = __builtin_amdgcn_exp2f(mrun[jj] - mn);
;                 mrun[jj] = mn;
;                 float rsum = 0.f;
; #pragma unroll
;                 for (int kt = 0; kt < 2; ++kt)
; #pragma unroll
;                     for (int e = 0; e < 4; ++e) { s[jj][kt][e] = __builtin_amdgcn_exp2f(s[jj][kt][e] - mn); rsum += s[jj][kt][e]; }
;                 lrun[jj] = lrun[jj] * alpha + rsum;
; #pragma unroll
;                 for (int dt = 0; dt < 4; ++dt) o[jj][dt] *= alpha;
;                 pw[jj].x = cvtpk(s[jj][0][0], s[jj][0][1]); pw[jj].y = cvtpk(s[jj][0][2], s[jj][0][3]); pw[jj].z = cvtpk(s[jj][1][0], s[jj][1][1]); pw[jj].w = cvtpk(s[jj][1][2], s[jj][1][3]);
;             }
; #pragma unroll
;             for (int jj = 0; jj < 2; ++jj)
; #pragma unroll
;                 for (int dt = 0; dt < 4; ++dt) {
;                     const bf16x8 vf = (bf16x8){vlo[jj][dt][0], vlo[jj][dt][1], vlo[jj][dt][2], vlo[jj][dt][3], vhi[jj][dt][0], vhi[jj][dt][1], vhi[jj][dt][2], vhi[jj][dt][3]};
;                     o[jj][dt] = __builtin_amdgcn_mfma_f32_16x16x32_bf16(vf, __builtin_bit_cast(bf16x8, pw[jj]), o[jj][dt], 0, 0, 0); }
	v_pk_add_f32 v[164:165], v[112:113], v[164:165]
	v_pk_add_f32 v[162:163], v[110:111], v[162:163]
	s_nop 1
	v_mfma_f32_16x16x32_bf16 v[130:133], v[130:133], v[30:33], v[162:165]
	s_nop 2
	v_pk_add_f32 v[164:165], v[114:115], v[168:169]
	v_pk_add_f32 v[162:163], v[108:109], v[166:167]
	v_mfma_f32_16x16x32_bf16 v[130:133], v[138:141], v[26:29], v[130:133]
	v_pk_add_f32 v[140:141], v[106:107], v[172:173]
	v_pk_add_f32 v[138:139], v[102:103], v[170:171]
	v_mfma_f32_16x16x32_bf16 v[134:137], v[134:137], v[30:33], v[162:165]
	v_mfma_f32_16x16x32_bf16 v[134:137], v[142:145], v[26:29], v[134:137]
	s_nop 2
	v_maximum3_f32 v129, v130, v131, v132
	v_pk_add_f32 v[164:165], v[104:105], v[176:177]
	v_pk_add_f32 v[162:163], v[100:101], v[174:175]
	v_mfma_f32_16x16x32_bf16 v[138:141], v[146:149], v[22:25], v[138:141]
	v_mfma_f32_16x16x32_bf16 v[138:141], v[154:157], v[18:21], v[138:141]
	v_maximum3_f32 v142, v133, v134, v135
	v_maximum3_f32 v143, v136, v137, v137
	v_maximum3_f32 v129, v129, v142, v143
	v_mov_b32_e32 v142, v129
	s_nop 1
	v_permlane16_swap_b32_e32 v129, v142
	v_maximum3_f32 v129, v129, v142, v142
	v_mov_b32_e32 v142, v129
	s_nop 1
	v_permlane32_swap_b32_e32 v129, v142
	v_maximum3_f32 v129, v125, v129, v142
	v_mfma_f32_16x16x32_bf16 v[142:145], v[150:153], v[22:25], v[162:165]
	v_pk_add_f32 v[130:131], v[130:131], v[128:129] op_sel:[0,1] op_sel_hi:[1,1] neg_lo:[0,1] neg_hi:[0,1]
	v_pk_add_f32 v[132:133], v[132:133], v[128:129] op_sel:[0,1] op_sel_hi:[1,1] neg_lo:[0,1] neg_hi:[0,1]
	v_pk_add_f32 v[134:135], v[134:135], v[128:129] op_sel:[0,1] op_sel_hi:[1,1] neg_lo:[0,1] neg_hi:[0,1]
	v_pk_add_f32 v[136:137], v[136:137], v[128:129] op_sel:[0,1] op_sel_hi:[1,1] neg_lo:[0,1] neg_hi:[0,1]
	v_sub_f32_e32 v125, v125, v129
	v_mfma_f32_16x16x32_bf16 v[142:145], v[158:161], v[18:21], v[142:145]
	v_exp_f32_e32 v146, v130
	v_exp_f32_e32 v148, v131
	v_exp_f32_e32 v150, v132
	v_exp_f32_e32 v152, v133
	v_exp_f32_e32 v154, v135
	v_exp_f32_e32 v156, v136
	v_exp_f32_e32 v158, v137
	v_exp_f32_e32 v134, v134
	v_exp_f32_e32 v136, v125
	v_maximum3_f32 v125, v138, v139, v140
	v_maximum3_f32 v133, v141, v142, v143
	v_maximum3_f32 v135, v144, v145, v145
	v_maximum3_f32 v125, v125, v133, v135
	v_mov_b32_e32 v133, v125
	s_nop 1
	v_permlane16_swap_b32_e32 v125, v133
	v_maximum3_f32 v125, v125, v133, v133
	v_mov_b32_e32 v133, v125
	s_nop 1
	v_permlane32_swap_b32_e32 v125, v133
	v_maximum3_f32 v160, v124, v125, v133
	v_pk_add_f32 v[138:139], v[138:139], v[160:161] op_sel_hi:[1,0] neg_lo:[0,1] neg_hi:[0,1]
	v_pk_add_f32 v[140:141], v[140:141], v[160:161] op_sel_hi:[1,0] neg_lo:[0,1] neg_hi:[0,1]
	v_pk_add_f32 v[142:143], v[142:143], v[160:161] op_sel_hi:[1,0] neg_lo:[0,1] neg_hi:[0,1]
	v_pk_add_f32 v[144:145], v[144:145], v[160:161] op_sel_hi:[1,0] neg_lo:[0,1] neg_hi:[0,1]
	v_sub_f32_e32 v137, v124, v160
	v_exp_f32_e32 v147, v138
	v_pk_mul_f32 v[56:57], v[56:57], v[136:137] op_sel_hi:[1,0]
	v_exp_f32_e32 v149, v139
	v_pk_mul_f32 v[54:55], v[54:55], v[136:137] op_sel_hi:[1,0]
	v_exp_f32_e32 v151, v140
	v_pk_mul_f32 v[64:65], v[64:65], v[136:137] op_sel_hi:[1,0]
	v_exp_f32_e32 v153, v141
	v_pk_mul_f32 v[62:63], v[62:63], v[136:137] op_sel_hi:[1,0]
	v_exp_f32_e32 v155, v143
	v_pk_mul_f32 v[60:61], v[60:61], v[136:137] op_sel_hi:[1,0]
	v_exp_f32_e32 v157, v144
	v_pk_mul_f32 v[58:59], v[58:59], v[136:137] op_sel_hi:[1,0]
	v_exp_f32_e32 v159, v145
	v_pk_mul_f32 v[52:53], v[52:53], v[136:137] op_sel_hi:[1,0]
	v_exp_f32_e32 v135, v142
	v_pk_mul_f32 v[50:51], v[50:51], v[136:137] op_sel_hi:[1,0]
	v_exp_f32_e32 v137, v137
	v_cvt_pk_bf16_f32 v130, v146, v148
	v_cvt_pk_bf16_f32 v131, v150, v152
	v_cvt_pk_bf16_f32 v132, v134, v154
	v_cvt_pk_bf16_f32 v133, v156, v158
	s_waitcnt lgkmcnt(12)
	v_mfma_f32_16x16x32_bf16 v[62:65], v[74:77], v[130:133], v[62:65]
	v_pk_add_f32 v[124:125], v[146:147], v[148:149]
	v_pk_mul_f32 v[48:49], v[48:49], v[136:137] op_sel:[0,1] op_sel_hi:[1,1]
	s_waitcnt lgkmcnt(10)
	v_mfma_f32_16x16x32_bf16 v[58:61], v[70:73], v[130:133], v[58:61]
	v_pk_mul_f32 v[46:47], v[46:47], v[136:137] op_sel:[0,1] op_sel_hi:[1,1]
	v_cvt_pk_bf16_f32 v70, v147, v149
	v_cvt_pk_bf16_f32 v71, v151, v153
	v_cvt_pk_bf16_f32 v72, v135, v155
	v_cvt_pk_bf16_f32 v73, v157, v159
	v_mfma_f32_16x16x32_bf16 v[54:57], v[78:81], v[130:133], v[54:57]
	v_pk_add_f32 v[78:79], v[150:151], v[124:125]
	v_pk_add_f32 v[78:79], v[152:153], v[78:79]
	s_waitcnt lgkmcnt(6)
	v_mfma_f32_16x16x32_bf16 v[46:49], v[14:17], v[70:73], v[46:49]
	v_pk_mul_f32 v[16:17], v[44:45], v[136:137] op_sel:[0,1] op_sel_hi:[1,1]
	v_pk_mul_f32 v[14:15], v[42:43], v[136:137] op_sel:[0,1] op_sel_hi:[1,1]
	v_pk_add_f32 v[74:75], v[134:135], v[78:79]
	v_mfma_f32_16x16x32_bf16 v[50:53], v[66:69], v[130:133], v[50:53]
	v_pk_add_f32 v[74:75], v[154:155], v[74:75]
	v_pk_add_f32 v[66:67], v[156:157], v[74:75]
	s_waitcnt lgkmcnt(4)
	v_mfma_f32_16x16x32_bf16 v[42:45], v[10:13], v[70:73], v[14:17]
	v_pk_mul_f32 v[12:13], v[40:41], v[136:137] op_sel:[0,1] op_sel_hi:[1,1]
	v_pk_mul_f32 v[10:11], v[38:39], v[136:137] op_sel:[0,1] op_sel_hi:[1,1]
	v_pk_add_f32 v[14:15], v[158:159], v[66:67]
	s_waitcnt lgkmcnt(2)
	v_mfma_f32_16x16x32_bf16 v[38:41], v[6:9], v[70:73], v[10:13]
	v_pk_mul_f32 v[8:9], v[36:37], v[136:137] op_sel:[0,1] op_sel_hi:[1,1]
	v_pk_mul_f32 v[6:7], v[34:35], v[136:137] op_sel:[0,1] op_sel_hi:[1,1]
	v_pk_fma_f32 v[98:99], v[98:99], v[136:137], v[14:15]
	s_waitcnt lgkmcnt(0)
	v_mfma_f32_16x16x32_bf16 v[34:37], v[2:5], v[70:73], v[6:9]
	v_mov_b32_e32 v125, v129
	v_mov_b32_e32 v124, v160
	s_branch .LBB0_300
